# opt18
# baseline (speedup 1.0000x reference)
; template <bool PASS2>
; __device__ __forceinline__ void ssm_block(const P& p, int blk) {
;     ...
;       f32x16 d0, d1, d2, d3;
;       {
;         const f32x16 z = {0.f, 0.f, 0.f, 0.f, 0.f, 0.f, 0.f, 0.f, 0.f, 0.f, 0.f, 0.f, 0.f, 0.f, 0.f, 0.f};
;         d0 = __builtin_amdgcn_mfma_f32_32x32x16_bf16(ua, bbf[0], z, 0, 0, 0);
;         d1 = __builtin_amdgcn_mfma_f32_32x32x16_bf16(ua, bbf[1], z, 0, 0, 0);
;         d2 = __builtin_amdgcn_mfma_f32_32x32x16_bf16(ua, bbf[2], z, 0, 0, 0);
;         d3 = __builtin_amdgcn_mfma_f32_32x32x16_bf16(ua, bbf[3], z, 0, 0, 0);
;       }
; #pragma unroll
;       for (int r = 0; r < 16; ++r) {
;         auto s01 = __builtin_amdgcn_permlane32_swap(__float_as_uint(d0[r]), __float_as_uint(d1[r]), false, false);
;         d0[r] = __uint_as_float(s01[0]); d1[r] = __uint_as_float(s01[1]);
;         auto s23 = __builtin_amdgcn_permlane32_swap(__float_as_uint(d2[r]), __float_as_uint(d3[r]), false, false);
;         d2[r] = __uint_as_float(s23[0]); d3[r] = __uint_as_float(s23[1]);
;       }
; #pragma unroll
;       for (int t = 0; t < 32; ++t) {
;         const int r = (t & 3) + 4 * (t >> 3);
;         const float bur = ((t >> 2) & 1) ? d1[r] : d0[r];
;         const float bui = ((t >> 2) & 1) ? d3[r] : d2[r];
;         const float nr = lr * xr - li * xi + bur, ni = lr * xi + li * xr + bui;
;         xr = nr; xi = ni;
;         if (PASS2) { xs[t * XS_STRIDE + lane] = f2bf(xr); xs[t * XS_STRIDE + 64 + lane] = f2bf(xi); }
;       }
.LBB0_355:
	v_mov_b32_e32 v132, 0
	v_mov_b32_e32 v133, 0
	v_mov_b32_e32 v134, 0
	v_mov_b32_e32 v135, 0
	v_mov_b32_e32 v136, 0
	v_mov_b32_e32 v137, 0
	v_mov_b32_e32 v138, 0
	v_mov_b32_e32 v139, 0
	v_lshl_add_u64 v[140:141], v[114:115], 0, s[34:35]
	s_and_saveexec_b64 s[36:37], s[4:5]
	v_add_co_u32_e32 v142, vcc, 0xad00000, v140
	s_nop 1
	v_addc_co_u32_e32 v143, vcc, 0, v141, vcc
	global_load_dwordx4 v[132:135], v[142:143], off offset:3072
	v_add_co_u32_e32 v142, vcc, 0xad20000, v140
	s_nop 1
	v_addc_co_u32_e32 v143, vcc, 0, v141, vcc
	global_load_dwordx4 v[136:139], v[142:143], off offset:3072
	s_or_b64 exec, exec, s[36:37]
	v_mfma_f32_32x32x16_bf16 v[48:63], v[0:3], v[64:67], 0
	v_mul_f32_e32 v131, v119, v125
	v_fma_f32 v131, v118, v124, -v131
	v_mul_f32_e32 v125, v118, v125
	v_fmac_f32_e32 v125, v119, v124
	v_mfma_f32_32x32x16_bf16 v[16:31], v[0:3], v[68:71], 0
	v_mfma_f32_32x32x16_bf16 v[32:47], v[0:3], v[72:75], 0
	s_nop 10
	v_permlane32_swap_b32_e32 v48, v16
	v_add_f32_e32 v48, v131, v48
	v_cvt_pk_bf16_f32 v124, v48, s0
	ds_write_b16 v128, v124
	v_permlane32_swap_b32_e32 v49, v17
	v_mfma_f32_32x32x16_bf16 v[0:15], v[0:3], v[76:79], 0
	v_permlane32_swap_b32_e32 v50, v18
	v_permlane32_swap_b32_e32 v51, v19
	v_permlane32_swap_b32_e32 v52, v20
	v_permlane32_swap_b32_e32 v53, v21
	s_nop 7
	v_permlane32_swap_b32_e32 v32, v0
	v_add_f32_e32 v32, v125, v32
	v_cvt_pk_bf16_f32 v124, v32, s0
	ds_write_b16 v128, v124 offset:128
	v_mul_f32_e32 v124, v119, v32
	v_fma_f32 v124, v118, v48, -v124
	v_mul_f32_e32 v32, v118, v32
	v_permlane32_swap_b32_e32 v33, v1
	v_add_f32_e32 v49, v124, v49
	v_fmac_f32_e32 v32, v119, v48
	v_add_f32_e32 v32, v32, v33
	v_cvt_pk_bf16_f32 v33, v49, v32
	ds_write_b16 v128, v33 offset:272
	ds_write_b16_d16_hi v128, v33 offset:400
	v_mul_f32_e32 v33, v119, v32
	v_fma_f32 v33, v118, v49, -v33
	v_mul_f32_e32 v48, v119, v49
	v_permlane32_swap_b32_e32 v34, v2
	v_add_f32_e32 v33, v33, v50
	v_fmac_f32_e32 v48, v118, v32
	v_add_f32_e32 v32, v48, v34
	v_cvt_pk_bf16_f32 v34, v33, v32
	ds_write_b16 v128, v34 offset:544
	ds_write_b16_d16_hi v128, v34 offset:672
	v_mul_f32_e32 v34, v119, v32
	v_fma_f32 v34, v118, v33, -v34
	v_mul_f32_e32 v33, v119, v33
	v_permlane32_swap_b32_e32 v35, v3
	v_add_f32_e32 v34, v34, v51
	v_fmac_f32_e32 v33, v118, v32
	v_add_f32_e32 v32, v33, v35
	v_cvt_pk_bf16_f32 v33, v34, v32
	ds_write_b16 v128, v33 offset:816
	ds_write_b16_d16_hi v128, v33 offset:944
	v_fma_f32 v33, -v119, v32, v16
	v_fma_f32 v16, v118, v34, v33
	v_mul_f32_e32 v33, v119, v34
	v_fmac_f32_e32 v33, v118, v32
	v_add_f32_e32 v0, v33, v0
	v_cvt_pk_bf16_f32 v32, v16, v0
	ds_write_b16 v128, v32 offset:1088
	ds_write_b16_d16_hi v128, v32 offset:1216
	v_mul_f32_e32 v32, v119, v0
	v_fma_f32 v32, v118, v16, -v32
	v_fma_f32 v16, v119, v16, v1
	v_add_f32_e32 v17, v32, v17
	v_fma_f32 v0, v118, v0, v16
	v_cvt_pk_bf16_f32 v1, v17, v0
	ds_write_b16 v128, v1 offset:1360
	ds_write_b16_d16_hi v128, v1 offset:1488
	v_fma_f32 v1, -v119, v0, v18
	v_fma_f32 v1, v118, v17, v1
	v_mul_f32_e32 v16, v119, v17
	v_fmac_f32_e32 v16, v118, v0
	v_add_f32_e32 v0, v16, v2
	v_cvt_pk_bf16_f32 v2, v1, v0
	ds_write_b16 v128, v2 offset:1632
	ds_write_b16_d16_hi v128, v2 offset:1760
	v_fma_f32 v2, -v119, v0, v19
	v_fma_f32 v2, v118, v1, v2
	v_fma_f32 v1, v119, v1, v3
	v_fma_f32 v0, v118, v0, v1
	v_cvt_pk_bf16_f32 v1, v2, v0
	ds_write_b16 v128, v1 offset:1904
	ds_write_b16_d16_hi v128, v1 offset:2032
	v_fma_f32 v1, -v119, v0, v52
	v_fma_f32 v1, v118, v2, v1
	v_mul_f32_e32 v2, v119, v2
	v_permlane32_swap_b32_e32 v36, v4
	v_fmac_f32_e32 v2, v118, v0
	v_add_f32_e32 v0, v2, v36
	v_cvt_pk_bf16_f32 v2, v1, v0
	ds_write_b16 v128, v2 offset:2176
	ds_write_b16_d16_hi v128, v2 offset:2304
	v_fma_f32 v2, -v119, v0, v53
	v_fma_f32 v2, v118, v1, v2
	v_mul_f32_e32 v1, v119, v1
	v_permlane32_swap_b32_e32 v37, v5
	v_fmac_f32_e32 v1, v118, v0
	v_add_f32_e32 v0, v1, v37
	v_cvt_pk_bf16_f32 v1, v2, v0
	ds_write_b16 v128, v1 offset:2448
	ds_write_b16_d16_hi v128, v1 offset:2576
	v_permlane32_swap_b32_e32 v54, v22
	v_fma_f32 v1, -v119, v0, v54
	v_fma_f32 v1, v118, v2, v1
	v_mul_f32_e32 v2, v119, v2
	v_permlane32_swap_b32_e32 v38, v6
	v_fmac_f32_e32 v2, v118, v0
	v_add_f32_e32 v0, v2, v38
	v_cvt_pk_bf16_f32 v2, v1, v0
	ds_write_b16 v128, v2 offset:2720
	ds_write_b16_d16_hi v128, v2 offset:2848
	v_permlane32_swap_b32_e32 v55, v23
	v_fma_f32 v2, -v119, v0, v55
	v_fma_f32 v2, v118, v1, v2
	v_mul_f32_e32 v1, v119, v1
	v_permlane32_swap_b32_e32 v39, v7
	v_fmac_f32_e32 v1, v118, v0
	v_add_f32_e32 v0, v1, v39
	v_cvt_pk_bf16_f32 v1, v2, v0
	ds_write_b16 v128, v1 offset:2992
	ds_write_b16_d16_hi v128, v1 offset:3120
	v_fma_f32 v1, -v119, v0, v20
	v_fma_f32 v1, v118, v2, v1
	v_fma_f32 v2, v119, v2, v4
	v_fma_f32 v0, v118, v0, v2
	v_cvt_pk_bf16_f32 v2, v1, v0
	ds_write_b16 v128, v2 offset:3264
	ds_write_b16_d16_hi v128, v2 offset:3392
	v_fma_f32 v2, -v119, v0, v21
	v_fma_f32 v2, v118, v1, v2
	v_fma_f32 v1, v119, v1, v5
	v_fma_f32 v0, v118, v0, v1
	v_cvt_pk_bf16_f32 v1, v2, v0
	ds_write_b16 v128, v1 offset:3536
	ds_write_b16_d16_hi v128, v1 offset:3664
	v_fma_f32 v1, -v119, v0, v22
	v_fma_f32 v1, v118, v2, v1
	v_fma_f32 v2, v119, v2, v6
	v_fma_f32 v0, v118, v0, v2
	v_cvt_pk_bf16_f32 v2, v1, v0
	ds_write_b16 v128, v2 offset:3808
	ds_write_b16_d16_hi v128, v2 offset:3936
	v_fma_f32 v2, -v119, v0, v23
	v_fma_f32 v2, v118, v1, v2
	v_fma_f32 v1, v119, v1, v7
	v_fma_f32 v0, v118, v0, v1
	v_cvt_pk_bf16_f32 v1, v2, v0
	ds_write_b16 v128, v1 offset:4080
	ds_write_b16_d16_hi v128, v1 offset:4208
	v_permlane32_swap_b32_e32 v56, v24
	v_fma_f32 v1, -v119, v0, v56
	v_fma_f32 v1, v118, v2, v1
	v_mul_f32_e32 v2, v119, v2
; template <bool PASS2>
; __device__ __forceinline__ void ssm_block(const P& p, int blk) {
;     ...
;       for (int t = 0; t < 32; ++t) {
;         const int r = (t & 3) + 4 * (t >> 3);
;         const float bur = ((t >> 2) & 1) ? d1[r] : d0[r];
;         const float bui = ((t >> 2) & 1) ? d3[r] : d2[r];
;         const float nr = lr * xr - li * xi + bur, ni = lr * xi + li * xr + bui;
;         xr = nr; xi = ni;
;         if (PASS2) { xs[t * XS_STRIDE + lane] = f2bf(xr); xs[t * XS_STRIDE + 64 + lane] = f2bf(xi); }
;       }
;     ...
;             bf16x8 af = *(const bf16x8*)(xs + (rt * 16 + l15) * XS_STRIDE + kk * 32 + q4 * 8);
	v_permlane32_swap_b32_e32 v40, v8
	v_fmac_f32_e32 v2, v118, v0
	v_add_f32_e32 v0, v2, v40
	v_cvt_pk_bf16_f32 v2, v1, v0
	ds_write_b16 v128, v2 offset:4352
	ds_write_b16_d16_hi v128, v2 offset:4480
	v_permlane32_swap_b32_e32 v57, v25
	v_fma_f32 v2, -v119, v0, v57
	v_fma_f32 v2, v118, v1, v2
	v_mul_f32_e32 v1, v119, v1
	v_permlane32_swap_b32_e32 v41, v9
	v_fmac_f32_e32 v1, v118, v0
	v_add_f32_e32 v0, v1, v41
	v_cvt_pk_bf16_f32 v1, v2, v0
	ds_write_b16 v128, v1 offset:4624
	ds_write_b16_d16_hi v128, v1 offset:4752
	v_permlane32_swap_b32_e32 v58, v26
	v_fma_f32 v1, -v119, v0, v58
	v_fma_f32 v1, v118, v2, v1
	v_mul_f32_e32 v2, v119, v2
	v_permlane32_swap_b32_e32 v42, v10
	v_fmac_f32_e32 v2, v118, v0
	v_add_f32_e32 v0, v2, v42
	v_cvt_pk_bf16_f32 v2, v1, v0
	ds_write_b16 v128, v2 offset:4896
	ds_write_b16_d16_hi v128, v2 offset:5024
	v_permlane32_swap_b32_e32 v59, v27
	v_fma_f32 v2, -v119, v0, v59
	v_fma_f32 v2, v118, v1, v2
	v_mul_f32_e32 v1, v119, v1
	v_permlane32_swap_b32_e32 v43, v11
	v_fmac_f32_e32 v1, v118, v0
	v_add_f32_e32 v0, v1, v43
	v_cvt_pk_bf16_f32 v1, v2, v0
	ds_write_b16 v128, v1 offset:5168
	ds_write_b16_d16_hi v128, v1 offset:5296
	v_fma_f32 v1, -v119, v0, v24
	v_fma_f32 v1, v118, v2, v1
	v_fma_f32 v2, v119, v2, v8
	v_fma_f32 v0, v118, v0, v2
	v_cvt_pk_bf16_f32 v2, v1, v0
	ds_write_b16 v128, v2 offset:5440
	ds_write_b16_d16_hi v128, v2 offset:5568
	v_fma_f32 v2, -v119, v0, v25
	v_fma_f32 v2, v118, v1, v2
	v_fma_f32 v1, v119, v1, v9
	v_fma_f32 v0, v118, v0, v1
	v_cvt_pk_bf16_f32 v1, v2, v0
	ds_write_b16 v128, v1 offset:5712
	ds_write_b16_d16_hi v128, v1 offset:5840
	v_fma_f32 v1, -v119, v0, v26
	v_fma_f32 v1, v118, v2, v1
	v_fma_f32 v2, v119, v2, v10
	v_fma_f32 v0, v118, v0, v2
	v_cvt_pk_bf16_f32 v2, v1, v0
	ds_write_b16 v128, v2 offset:5984
	ds_write_b16_d16_hi v128, v2 offset:6112
	v_fma_f32 v2, -v119, v0, v27
	v_fma_f32 v2, v118, v1, v2
	v_fma_f32 v1, v119, v1, v11
	v_fma_f32 v0, v118, v0, v1
	v_cvt_pk_bf16_f32 v1, v2, v0
	ds_write_b16 v128, v1 offset:6256
	ds_write_b16_d16_hi v128, v1 offset:6384
	v_permlane32_swap_b32_e32 v60, v28
	v_fma_f32 v1, -v119, v0, v60
	v_fma_f32 v1, v118, v2, v1
	v_mul_f32_e32 v2, v119, v2
	v_permlane32_swap_b32_e32 v44, v12
	v_fmac_f32_e32 v2, v118, v0
	v_add_f32_e32 v0, v2, v44
	v_cvt_pk_bf16_f32 v2, v1, v0
	ds_write_b16 v128, v2 offset:6528
	ds_write_b16_d16_hi v128, v2 offset:6656
	v_permlane32_swap_b32_e32 v61, v29
	v_fma_f32 v2, -v119, v0, v61
	v_fma_f32 v2, v118, v1, v2
	v_mul_f32_e32 v1, v119, v1
	v_permlane32_swap_b32_e32 v45, v13
	v_fmac_f32_e32 v1, v118, v0
	v_add_f32_e32 v0, v1, v45
	v_cvt_pk_bf16_f32 v1, v2, v0
	ds_write_b16 v128, v1 offset:6800
	ds_write_b16_d16_hi v128, v1 offset:6928
	v_permlane32_swap_b32_e32 v62, v30
	v_fma_f32 v1, -v119, v0, v62
	v_fma_f32 v1, v118, v2, v1
	v_mul_f32_e32 v2, v119, v2
	v_permlane32_swap_b32_e32 v46, v14
	v_fmac_f32_e32 v2, v118, v0
	v_add_f32_e32 v0, v2, v46
	v_cvt_pk_bf16_f32 v2, v1, v0
	ds_write_b16 v128, v2 offset:7072
	ds_write_b16_d16_hi v128, v2 offset:7200
	v_permlane32_swap_b32_e32 v63, v31
	v_fma_f32 v2, -v119, v0, v63
	v_fma_f32 v2, v118, v1, v2
	v_mul_f32_e32 v1, v119, v1
	v_permlane32_swap_b32_e32 v47, v15
	v_fmac_f32_e32 v1, v118, v0
	v_add_f32_e32 v3, v1, v47
	v_cvt_pk_bf16_f32 v0, v2, v3
	ds_write_b16 v128, v0 offset:7344
	ds_write_b16_d16_hi v128, v0 offset:7472
	v_mul_f32_e32 v0, v119, v3
	v_mul_f32_e32 v1, v119, v2
	v_fma_f32 v0, v118, v2, -v0
	v_fmac_f32_e32 v1, v118, v3
	v_mov_b32_e32 v2, v28
	v_mov_b32_e32 v3, v12
	v_pk_add_f32 v[0:1], v[0:1], v[2:3]
	v_mov_b32_e32 v12, v29
	v_cvt_pk_bf16_f32 v2, v0, s0
	ds_write_b16 v128, v2 offset:7616
	v_cvt_pk_bf16_f32 v2, v1, s0
	ds_write_b16 v128, v2 offset:7744
	v_pk_mul_f32 v[2:3], v[122:123], v[0:1]
	v_mov_b32_e32 v4, v30
	v_pk_fma_f32 v[6:7], v[120:121], v[0:1], v[2:3] op_sel:[0,0,1] op_sel_hi:[1,1,0] neg_lo:[0,0,1] neg_hi:[0,0,1]
	v_pk_fma_f32 v[0:1], v[120:121], v[0:1], v[2:3] op_sel:[0,0,1] op_sel_hi:[1,1,0]
	v_mov_b32_e32 v5, v14
	v_mov_b32_e32 v7, v1
	v_pk_add_f32 v[0:1], v[6:7], v[12:13]
	v_mov_b32_e32 v14, v31
	v_cvt_pk_bf16_f32 v2, v0, s0
	ds_write_b16 v128, v2 offset:7888
	v_cvt_pk_bf16_f32 v2, v1, s0
	ds_write_b16 v128, v2 offset:8016
	v_pk_mul_f32 v[2:3], v[122:123], v[0:1]
	s_nop 0
	v_pk_fma_f32 v[6:7], v[120:121], v[0:1], v[2:3] op_sel:[0,0,1] op_sel_hi:[1,1,0] neg_lo:[0,0,1] neg_hi:[0,0,1]
	v_pk_fma_f32 v[0:1], v[120:121], v[0:1], v[2:3] op_sel:[0,0,1] op_sel_hi:[1,1,0]
	s_nop 0
	v_mov_b32_e32 v7, v1
	v_pk_add_f32 v[0:1], v[6:7], v[4:5]
	s_nop 0
	v_cvt_pk_bf16_f32 v2, v0, s0
	ds_write_b16 v128, v2 offset:8160
	v_cvt_pk_bf16_f32 v2, v1, s0
	ds_write_b16 v128, v2 offset:8288
	v_pk_mul_f32 v[2:3], v[122:123], v[0:1]
	s_nop 0
	v_pk_fma_f32 v[4:5], v[120:121], v[0:1], v[2:3] op_sel:[0,0,1] op_sel_hi:[1,1,0] neg_lo:[0,0,1] neg_hi:[0,0,1]
	v_pk_fma_f32 v[0:1], v[120:121], v[0:1], v[2:3] op_sel:[0,0,1] op_sel_hi:[1,1,0]
	s_nop 0
	v_mov_b32_e32 v5, v1
	v_pk_add_f32 v[124:125], v[4:5], v[14:15]
	s_nop 0
	v_cvt_pk_bf16_f32 v0, v124, s0
	ds_write_b16 v128, v0 offset:8432
	v_cvt_pk_bf16_f32 v0, v125, s0
	ds_write_b16 v128, v0 offset:8560
	ds_read_b128 v[0:3], v130
	ds_read_b128 v[4:7], v130 offset:64
	s_waitcnt lgkmcnt(1)
; __device__ __forceinline__ float sigm(float x) { return __builtin_amdgcn_rcpf(1.f + __expf(-x)); }
; template <bool PASS2>
; __device__ __forceinline__ void ssm_block(const P& p, int blk) {
;     ...
; #pragma unroll
;         for (int rt = 0; rt < 2; ++rt) {
;           f32x4 acc = f32x4{0.f, 0.f, 0.f, 0.f};
; #pragma unroll
;           for (int kk = 0; kk < 4; ++kk) {
;             bf16x8 af = *(const bf16x8*)(xs + (rt * 16 + l15) * XS_STRIDE + kk * 32 + q4 * 8);
;             acc = __builtin_amdgcn_mfma_f32_16x16x32_bf16(af, cf[kk], acc, 0, 0, 0);
;           }
;           {
;             bf16x8 au = {0, 0, 0, 0, 0, 0, 0, 0};
;             if (q4 < 2) au = *(const bf16x8*)(proj + (size_t)(sc * 32 + rt * 16 + l15) * 4096 + 1536 + g * 16 + q4 * 8);
;             acc = __builtin_amdgcn_mfma_f32_16x16x32_bf16(au, df, acc, 0, 0, 0);
;           }
; #pragma unroll
;           for (int r = 0; r < 4; ++r) {
;             const int t = rt * 16 + q4 * 4 + r;
;             const float y = acc[r];
;             const float ge = y * sigm(1.5957691216057308f * (y + 0.044715f * y * y * y));
;             proj[(size_t)(sc * 32 + t) * 4096 + 1536 + g * 16 + l15] = f2bf(ge);
;           }
;         }
	v_mfma_f32_16x16x32_bf16 v[0:3], v[0:3], v[80:83], 0
	ds_read_b128 v[8:11], v130 offset:128
	s_waitcnt lgkmcnt(1)
	v_mfma_f32_16x16x32_bf16 v[0:3], v[4:7], v[84:87], v[0:3]
	ds_read_b128 v[4:7], v130 offset:192
	s_waitcnt vmcnt(1) lgkmcnt(1)
	v_mfma_f32_16x16x32_bf16 v[0:3], v[8:11], v[88:91], v[0:3]
	v_lshl_add_u64 v[10:11], v[114:115], 0, s[34:35]
	v_mov_b32_e32 v8, 0
	v_mov_b32_e32 v9, 0
	s_waitcnt vmcnt(0) lgkmcnt(0)
	v_mfma_f32_16x16x32_bf16 v[2:5], v[4:7], v[92:95], v[0:3]
	v_mov_b32_e32 v6, 0
	v_mov_b32_e32 v7, 0
	s_nop 0
	v_mov_b32_e32 v0, 0
	v_mfma_f32_16x16x32_bf16 v[2:5], v[132:135], v[96:99], v[2:5]
	v_lshl_add_u64 v[8:9], v[112:113], 0, s[34:35]
	ds_read_b128 v[20:23], v130 offset:4480
	ds_read_b128 v[16:19], v130 offset:4416
	s_nop 4
	v_mul_f32_e32 v1, 0x3d372713, v2
	v_mul_f32_e32 v1, v2, v1
	v_fma_f32 v1, v2, v1, v2
	v_mul_f32_e32 v1, 0x3fcc422a, v1
	v_mul_f32_e32 v1, 0xbfb8aa3b, v1
	v_mul_f32_e32 v6, 0x3d372713, v3
	v_exp_f32_e32 v1, v1
	v_mul_f32_e32 v6, v3, v6
	v_fma_f32 v6, v3, v6, v3
	v_mul_f32_e32 v6, 0x3fcc422a, v6
	v_mul_f32_e32 v6, 0xbfb8aa3b, v6
	v_add_f32_e32 v1, 1.0, v1
	v_exp_f32_e32 v6, v6
	v_rcp_f32_e32 v1, v1
	v_add_f32_e32 v6, 1.0, v6
	v_mul_f32_e32 v1, v2, v1
	v_mul_f32_e32 v2, 0x3d372713, v4
	v_rcp_f32_e32 v12, v6
	v_mul_f32_e32 v2, v4, v2
	v_add_co_u32_e32 v6, vcc, s38, v8
	v_fma_f32 v2, v4, v2, v4
	v_cvt_pk_bf16_f32 v1, v1, s0
	v_addc_co_u32_e32 v7, vcc, 0, v9, vcc
	v_mul_f32_e32 v2, 0x3fcc422a, v2
	global_store_short v[6:7], v1, off offset:3072
	v_mul_f32_e32 v2, 0xbfb8aa3b, v2
	v_mul_f32_e32 v7, 0x3d372713, v5
	v_mul_f32_e32 v1, v3, v12
	v_exp_f32_e32 v6, v2
	v_mul_f32_e32 v7, v5, v7
	ds_read_b128 v[12:15], v130 offset:4352
	v_fma_f32 v7, v5, v7, v5
	v_mul_f32_e32 v7, 0x3fcc422a, v7
	v_mul_f32_e32 v7, 0xbfb8aa3b, v7
	v_add_f32_e32 v6, 1.0, v6
	v_exp_f32_e32 v7, v7
	v_rcp_f32_e32 v6, v6
	v_add_co_u32_e32 v2, vcc, s39, v8
	v_cvt_pk_bf16_f32 v1, v1, s0
	s_nop 0
	v_addc_co_u32_e32 v3, vcc, 0, v9, vcc
	global_store_short v[2:3], v1, off offset:3072
	v_add_f32_e32 v2, 1.0, v7
	v_mul_f32_e32 v1, v4, v6
	v_rcp_f32_e32 v4, v2
	s_waitcnt lgkmcnt(0)
	v_mfma_f32_16x16x32_bf16 v[12:15], v[12:15], v[80:83], 0
	v_add_co_u32_e32 v2, vcc, s40, v8
	v_cvt_pk_bf16_f32 v1, v1, s0
	s_nop 0
	v_addc_co_u32_e32 v3, vcc, 0, v9, vcc
	global_store_short v[2:3], v1, off offset:3072
	v_mul_f32_e32 v1, v5, v4
	v_mfma_f32_16x16x32_bf16 v[2:5], v[16:19], v[84:87], v[12:15]
	v_add_co_u32_e32 v6, vcc, s41, v8
	v_cvt_pk_bf16_f32 v1, v1, s0
	s_nop 0
	ds_read_b128 v[12:15], v130 offset:4544
	v_mfma_f32_16x16x32_bf16 v[2:5], v[20:23], v[88:91], v[2:5]
	v_addc_co_u32_e32 v7, vcc, 0, v9, vcc
	global_store_short v[6:7], v1, off offset:3072
	s_waitcnt lgkmcnt(0)
	v_mfma_f32_16x16x32_bf16 v[4:7], v[12:15], v[92:95], v[2:5]
	v_mov_b32_e32 v1, 0
	s_nop 2
	v_mov_b32_e32 v2, 0
	v_mov_b32_e32 v3, 0
	s_branch .LBB0_352
